# attention: static s_setprio 1 for waves 4-7 during the attention phase
# speedup vs baseline: 1.0099x; 1.0093x over previous
; #define GRID_BAR() grid_bar(barw, xcc, bst, (unsigned)G, wave)
; __global__ void __launch_bounds__(512) mega(Args a) {
;     ...
;                 int vcu2 = vcu; asm volatile("" : "+s"(vcu2));
;                 for (int id = vcu2; id < 2560; id += G) {
;                     int qh, kv, row0, kvrow0, seq;
;                     if (id < 512) { kv = id >> 8; const int rem = id & 255; qh = kv * 4 + (rem >> 6); kvrow0 = 0; row0 = (rem & 63) * 256; seq = LP; }
;                     else { const int id2 = id - 512, gg = id2 >> 7, u = id2 & 127; kv = gg & 1; qh = kv * 4 + (u >> 5); kvrow0 = LP + (gg >> 1) * LS; row0 = kvrow0 + (u & 31) * 256; seq = LS; }
;                     attn::attn_dense_body<attn::bf16>((const attn::bf16*)QKV + (size_t)row0 * 1536 + qh * 128, (const attn::bf16*)QKV + (size_t)kvrow0 * 1536 + 1024 + kv * 128,
;                                                       (const attn::bf16*)QKV + (size_t)kvrow0 * 1536 + 1280 + kv * 128, HB + (size_t)row0 * DM + qh * 128, seq, (char*)lds, wave);
;                     __syncthreads();
;                 }
;             }
;             GRID_BAR();
.LBB0_564:
	v_readlane_b32 s48, v254, 6
	s_cmp_ge_u32 s1, 0x20400
	s_cbranch_scc0 .Lattn_noprio
	s_setprio 1
.Lattn_noprio:
	v_writelane_b32 v253, s52, 0
	v_writelane_b32 v253, s53, 1
	s_waitcnt lgkmcnt(0)
	s_barrier
	s_cmpk_gt_i32 s48, 0x9ff
	s_cbranch_scc0 .LBB0_570
.LBB0_565:
	s_waitcnt vmcnt(0) lgkmcnt(0)
	s_setprio 0
	v_readlane_b32 s52, v253, 0
	v_readlane_b32 s53, v253, 1
	s_and_b64 vcc, exec, s[36:37]
	s_barrier
	s_cbranch_vccnz .LBB0_620
	v_mbcnt_lo_u32_b32 v0, -1, 0
	v_mbcnt_hi_u32_b32 v0, -1, v0
	s_nop 0
	v_cmp_eq_u32_e32 vcc, 0, v0
	s_and_saveexec_b64 s[82:83], vcc
	s_cbranch_execz .LBB0_619
	v_readlane_b32 s2, v255, 55
	s_nop 1
	v_mov_b32_e32 v0, s2
	ds_read_b32 v1, v0
	v_readlane_b32 s2, v255, 56
	s_waitcnt lgkmcnt(0)
	v_cmp_ne_u32_e32 vcc, 0, v1
	v_mov_b32_e32 v0, s2
	ds_read_b32 v0, v0
	s_cbranch_vccnz .LBB0_597
	v_mov_b32_e32 v1, 0
	s_branch .LBB0_594
